# in-projection K-loop: the two loop-invariant LDS read base addresses kept in spare VGPRs instead of being recomputed twice per iteration
# baseline (speedup 1.0000x reference)
.LBB0_229:
	s_lshl_b32 s6, s6, 5
	s_mov_b64 s[86:87], 0x80
	s_and_b32 s33, s6, 0x60
	s_add_i32 m0, s62, 0x18000
	v_lshl_add_u64 v[6:7], v[6:7], 0, s[86:87]
	s_lshl_b32 s9, s3, 13
	s_lshl_b32 s34, s33, 7
	s_waitcnt vmcnt(4)
	s_barrier
	global_load_lds_dwordx4 v[6:7], off
	v_lshl_add_u64 v[4:5], v[4:5], 0, s[86:87]
	s_add_i32 m0, s62, 0x1a000
	s_add_i32 s67, s62, 0x8000
	s_add_i32 s68, s62, 0xa000
	global_load_lds_dwordx4 v[4:5], off
	v_lshl_add_u64 v[0:1], v[0:1], 0, s[86:87]
	s_mov_b32 m0, s67
	s_add_u32 s6, s28, 0x80080
	global_load_lds_dwordx4 v[0:1], off
	v_lshl_add_u64 v[0:1], v[2:3], 0, s[86:87]
	s_mov_b32 m0, s68
	s_addc_u32 s7, s29, 0
	global_load_lds_dwordx4 v[0:1], off
	s_add_i32 m0, s62, 0x1c000
	v_lshl_add_u64 v[0:1], s[6:7], 0, v[184:185]
	global_load_lds_dwordx4 v[0:1], off
	v_lshl_add_u64 v[0:1], s[6:7], 0, v[188:189]
	s_add_i32 m0, s62, 0x1e000
	v_lshlrev_b32_e32 v2, 2, v210
	global_load_lds_dwordx4 v[0:1], off
	v_lshlrev_b32_e32 v0, 1, v8
	v_lshl_or_b32 v1, v210, 6, v0
	v_or_b32_e32 v0, v0, v218
	v_and_b32_e32 v2, 32, v2
	v_bitop3_b32 v165, s34, v0, v219 bitop3:0xf6
	v_lshlrev_b32_e32 v0, 9, v180
	v_bitop3_b32 v1, v1, s9, v2 bitop3:0xde
	v_and_b32_e32 v0, 0xffff0000, v0
	v_lshlrev_b32_e32 v2, 12, v216
	v_or3_b32 v0, v214, v0, v2
	v_add_u32_e32 v132, v0, v215
	v_lshlrev_b32_e32 v0, 5, v217
	s_waitcnt vmcnt(6)
	v_and_b32_e32 v0, 0xffff0000, v0
	v_readlane_b32 s6, v254, 8
	v_or3_b32 v0, v214, v0, v2
	s_add_i32 s84, 0, 0x10000
	s_add_i32 s85, 0, 0x14000
	v_lshl_or_b32 v129, s3, 6, v210
	s_ashr_i32 s69, s6, 31
	s_mov_b32 s80, s6
	s_ashr_i32 s81, s2, 31
	v_or_b32_e32 v166, s33, v8
	v_mov_b32_e32 v133, v131
	v_add_u32_e32 v134, v0, v215
	v_mov_b32_e32 v135, v131
	v_add_u32_e32 v167, s84, v165
	v_add_u32_e32 v168, 0, v1
	v_add_u32_e32 v169, s85, v165
	s_mov_b32 s88, 0xbfb8aa3b
	s_mov_b32 s90, 0x3dd2d3e7
	v_mov_b32_e32 v170, 0xbdd2d3e7
	s_barrier
	v_readlane_b32 s7, v254, 9
	s_waitcnt vmcnt(0)
	v_add_u32_e32 v171, 0x18000, v165
	v_add_u32_e32 v255, 0x1c000, v165
	s_branch .LBB0_231

.LBB0_233:
	v_mov_b64_e32 v[0:1], 0x5a0
	s_ashr_i32 s95, s94, 31
	v_cmp_lt_i64_e32 vcc, s[34:35], v[0:1]
	s_lshl_b64 s[34:35], s[94:95], 20
	s_add_u32 s96, s56, s34
	s_addc_u32 s97, s57, s35
	s_and_b64 s[34:35], vcc, exec
	s_cselect_b32 s9, s97, s11
	s_cselect_b32 s89, s96, s10
	s_ashr_i32 s71, s70, 31
	s_lshl_b64 s[34:35], s[70:71], 20
	s_add_u32 s98, s82, s34
	s_addc_u32 s99, s83, s35
	s_and_b64 s[34:35], vcc, exec
	s_cselect_b32 s71, s99, s29
	s_cselect_b32 s91, s98, s28
	s_add_u32 s10, s10, 0x80080
	s_addc_u32 s11, s11, 0
	s_add_u32 s93, s28, 0x100
	s_addc_u32 s95, s29, 0
	s_mov_b32 vcc_lo, -2
	ds_read_b128 v[136:139], v167
	ds_read_b128 v[140:143], v167 offset:1024
	ds_read_b128 v[144:147], v167 offset:2048
	ds_read_b128 v[148:151], v167 offset:3072
	s_add_u32 s3, s10, 0xfff80080
	s_addc_u32 s28, s11, -1
	s_cmp_eq_u32 vcc_lo, 28
	s_cselect_b32 s35, s9, s28
	s_cselect_b32 s34, s89, s3
	s_cselect_b32 s29, s71, s95
	s_cselect_b32 s28, s91, s93
	v_lshl_add_u64 v[152:153], s[10:11], 0, v[132:133]
	s_add_i32 m0, s62, 0xc000
	ds_read_b128 v[172:175], v168
	ds_read_b128 v[190:193], v168 offset:1024
	ds_read_b128 v[194:197], v168 offset:2048
	ds_read_b128 v[198:201], v168 offset:3072
	ds_read_b128 v[202:205], v168 offset:4096
	ds_read_b128 v[206:209], v168 offset:5120
	ds_read_b128 v[224:227], v168 offset:6144
	ds_read_b128 v[228:231], v168 offset:7168
	global_load_lds_dwordx4 v[152:153], off
	s_add_i32 m0, s62, 0xe000
	v_lshl_add_u64 v[152:153], s[10:11], 0, v[134:135]
	global_load_lds_dwordx4 v[152:153], off
	s_waitcnt lgkmcnt(8)
	s_barrier
	s_waitcnt lgkmcnt(0)
	v_mfma_f32_16x16x32_bf16 v[124:127], v[136:139], v[172:175], 0
	v_mfma_f32_16x16x32_bf16 v[116:119], v[144:147], v[172:175], 0
	v_mfma_f32_16x16x32_bf16 v[108:111], v[136:139], v[194:197], 0
	v_mfma_f32_16x16x32_bf16 v[100:103], v[144:147], v[194:197], 0
	v_mfma_f32_16x16x32_bf16 v[92:95], v[136:139], v[202:205], 0
	v_mfma_f32_16x16x32_bf16 v[84:87], v[144:147], v[202:205], 0
	v_mfma_f32_16x16x32_bf16 v[76:79], v[136:139], v[224:227], 0
	v_mfma_f32_16x16x32_bf16 v[68:71], v[144:147], v[224:227], 0
	v_mfma_f32_16x16x32_bf16 v[124:127], v[140:143], v[190:193], v[124:127]
	v_mfma_f32_16x16x32_bf16 v[116:119], v[148:151], v[190:193], v[116:119]
	v_mfma_f32_16x16x32_bf16 v[108:111], v[140:143], v[198:201], v[108:111]
	v_mfma_f32_16x16x32_bf16 v[100:103], v[148:151], v[198:201], v[100:103]
	v_mfma_f32_16x16x32_bf16 v[92:95], v[140:143], v[206:209], v[92:95]
	v_mfma_f32_16x16x32_bf16 v[84:87], v[148:151], v[206:209], v[84:87]
	v_mfma_f32_16x16x32_bf16 v[76:79], v[140:143], v[228:231], v[76:79]
	v_mfma_f32_16x16x32_bf16 v[68:71], v[148:151], v[228:231], v[68:71]
	s_barrier
	s_add_i32 s3, s84, s61
	v_lshl_add_u64 v[152:153], s[28:29], 0, v[184:185]
	s_mov_b32 m0, s3
	ds_read_b128 v[232:235], v169
	ds_read_b128 v[236:239], v169 offset:1024
	ds_read_b128 v[240:243], v169 offset:2048
	ds_read_b128 v[244:247], v169 offset:3072
	global_load_lds_dwordx4 v[152:153], off
	s_add_i32 m0, s3, 0x2000
	v_lshl_add_u64 v[248:249], s[28:29], 0, v[188:189]
	global_load_lds_dwordx4 v[248:249], off
	s_barrier
	s_waitcnt lgkmcnt(0)
	v_mfma_f32_16x16x32_bf16 v[120:123], v[232:235], v[172:175], 0
	v_mfma_f32_16x16x32_bf16 v[112:115], v[240:243], v[172:175], 0
	v_mfma_f32_16x16x32_bf16 v[104:107], v[232:235], v[194:197], 0
	v_mfma_f32_16x16x32_bf16 v[96:99], v[240:243], v[194:197], 0
	v_mfma_f32_16x16x32_bf16 v[88:91], v[232:235], v[202:205], 0
	v_mfma_f32_16x16x32_bf16 v[80:83], v[240:243], v[202:205], 0
	v_mfma_f32_16x16x32_bf16 v[72:75], v[232:235], v[224:227], 0
	v_mfma_f32_16x16x32_bf16 v[64:67], v[240:243], v[224:227], 0
	v_mfma_f32_16x16x32_bf16 v[120:123], v[236:239], v[190:193], v[120:123]
	v_mfma_f32_16x16x32_bf16 v[112:115], v[244:247], v[190:193], v[112:115]
	v_mfma_f32_16x16x32_bf16 v[104:107], v[236:239], v[198:201], v[104:107]
	v_mfma_f32_16x16x32_bf16 v[96:99], v[244:247], v[198:201], v[96:99]
	v_mfma_f32_16x16x32_bf16 v[88:91], v[236:239], v[206:209], v[88:91]
	v_mfma_f32_16x16x32_bf16 v[80:83], v[244:247], v[206:209], v[80:83]
	v_mfma_f32_16x16x32_bf16 v[72:75], v[236:239], v[228:231], v[72:75]
	v_mfma_f32_16x16x32_bf16 v[64:67], v[244:247], v[228:231], v[64:67]
	s_mov_b32 m0, s62
	v_lshl_add_u64 v[250:251], s[34:35], 0, v[182:183]
	s_barrier
	ds_read_b128 v[172:175], v168 offset:16384
	ds_read_b128 v[190:193], v168 offset:17408
	ds_read_b128 v[194:197], v168 offset:18432
	ds_read_b128 v[198:201], v168 offset:19456
	ds_read_b128 v[202:205], v168 offset:20480
	ds_read_b128 v[206:209], v168 offset:21504
	ds_read_b128 v[224:227], v168 offset:22528
	ds_read_b128 v[228:231], v168 offset:23552
	global_load_lds_dwordx4 v[250:251], off
	s_mov_b32 m0, s63
	v_lshl_add_u64 v[252:253], s[34:35], 0, v[186:187]
	global_load_lds_dwordx4 v[252:253], off
	s_barrier
	s_waitcnt lgkmcnt(0)
	v_mfma_f32_16x16x32_bf16 v[60:63], v[136:139], v[172:175], 0
	v_mfma_f32_16x16x32_bf16 v[52:55], v[144:147], v[172:175], 0
	v_mfma_f32_16x16x32_bf16 v[44:47], v[136:139], v[194:197], 0
	v_mfma_f32_16x16x32_bf16 v[36:39], v[144:147], v[194:197], 0
	v_mfma_f32_16x16x32_bf16 v[28:31], v[136:139], v[202:205], 0
	v_mfma_f32_16x16x32_bf16 v[20:23], v[144:147], v[202:205], 0
	v_mfma_f32_16x16x32_bf16 v[12:15], v[136:139], v[224:227], 0
	v_mfma_f32_16x16x32_bf16 v[4:7], v[144:147], v[224:227], 0
	v_mfma_f32_16x16x32_bf16 v[60:63], v[140:143], v[190:193], v[60:63]
	v_mfma_f32_16x16x32_bf16 v[52:55], v[148:151], v[190:193], v[52:55]
	v_mfma_f32_16x16x32_bf16 v[44:47], v[140:143], v[198:201], v[44:47]
	v_mfma_f32_16x16x32_bf16 v[36:39], v[148:151], v[198:201], v[36:39]
	v_mfma_f32_16x16x32_bf16 v[28:31], v[140:143], v[206:209], v[28:31]
	v_mfma_f32_16x16x32_bf16 v[20:23], v[148:151], v[206:209], v[20:23]
	v_mfma_f32_16x16x32_bf16 v[12:15], v[140:143], v[228:231], v[12:15]
	v_mfma_f32_16x16x32_bf16 v[4:7], v[148:151], v[228:231], v[4:7]
	s_barrier
	s_add_u32 s74, s28, 0x80000
	s_addc_u32 s75, s29, 0
	s_add_i32 s3, s85, s61
	s_mov_b32 m0, s3
	v_lshl_add_u64 v[136:137], s[74:75], 0, v[184:185]
	global_load_lds_dwordx4 v[136:137], off
	s_add_i32 m0, s3, 0x2000
	v_lshl_add_u64 v[136:137], s[74:75], 0, v[188:189]
	global_load_lds_dwordx4 v[136:137], off
	s_waitcnt vmcnt(6)
	s_barrier
	v_mfma_f32_16x16x32_bf16 v[56:59], v[232:235], v[172:175], 0
	v_mfma_f32_16x16x32_bf16 v[48:51], v[240:243], v[172:175], 0
	v_mfma_f32_16x16x32_bf16 v[40:43], v[232:235], v[194:197], 0
	v_mfma_f32_16x16x32_bf16 v[32:35], v[240:243], v[194:197], 0
	v_mfma_f32_16x16x32_bf16 v[24:27], v[232:235], v[202:205], 0
	v_mfma_f32_16x16x32_bf16 v[16:19], v[240:243], v[202:205], 0
	v_mfma_f32_16x16x32_bf16 v[8:11], v[232:235], v[224:227], 0
	v_mfma_f32_16x16x32_bf16 v[0:3], v[240:243], v[224:227], 0
	v_mfma_f32_16x16x32_bf16 v[56:59], v[236:239], v[190:193], v[56:59]
	v_mfma_f32_16x16x32_bf16 v[48:51], v[244:247], v[190:193], v[48:51]
	v_mfma_f32_16x16x32_bf16 v[40:43], v[236:239], v[198:201], v[40:43]
	v_mfma_f32_16x16x32_bf16 v[32:35], v[244:247], v[198:201], v[32:35]
	v_mfma_f32_16x16x32_bf16 v[24:27], v[236:239], v[206:209], v[24:27]
	v_mfma_f32_16x16x32_bf16 v[16:19], v[244:247], v[206:209], v[16:19]
	v_mfma_f32_16x16x32_bf16 v[8:11], v[236:239], v[228:231], v[8:11]
	v_mfma_f32_16x16x32_bf16 v[0:3], v[244:247], v[228:231], v[0:3]
	s_add_i32 s3, 0, 0x18000
	s_barrier
	ds_read_b128 v[136:139], v171
	ds_read_b128 v[140:143], v171 offset:1024
	ds_read_b128 v[144:147], v171 offset:2048
	ds_read_b128 v[148:151], v171 offset:3072
	s_add_u32 s34, s34, 0x80000
	s_addc_u32 s35, s35, 0
	s_mov_b32 m0, s64
	v_lshl_add_u64 v[232:233], s[34:35], 0, v[182:183]
	ds_read_b128 v[172:175], v168 offset:32768
	ds_read_b128 v[190:193], v168 offset:33792
	ds_read_b128 v[194:197], v168 offset:34816
	ds_read_b128 v[198:201], v168 offset:35840
	ds_read_b128 v[202:205], v168 offset:36864
	ds_read_b128 v[206:209], v168 offset:37888
	ds_read_b128 v[224:227], v168 offset:38912
	ds_read_b128 v[228:231], v168 offset:39936
	global_load_lds_dwordx4 v[232:233], off
	s_mov_b32 m0, s65
	v_lshl_add_u64 v[232:233], s[34:35], 0, v[186:187]
	global_load_lds_dwordx4 v[232:233], off
	s_waitcnt lgkmcnt(8)
	s_barrier
	s_waitcnt lgkmcnt(0)
	v_mfma_f32_16x16x32_bf16 v[124:127], v[136:139], v[172:175], v[124:127]
	v_mfma_f32_16x16x32_bf16 v[116:119], v[144:147], v[172:175], v[116:119]
	v_mfma_f32_16x16x32_bf16 v[108:111], v[136:139], v[194:197], v[108:111]
	v_mfma_f32_16x16x32_bf16 v[100:103], v[144:147], v[194:197], v[100:103]
	v_mfma_f32_16x16x32_bf16 v[92:95], v[136:139], v[202:205], v[92:95]
	v_mfma_f32_16x16x32_bf16 v[84:87], v[144:147], v[202:205], v[84:87]
	v_mfma_f32_16x16x32_bf16 v[76:79], v[136:139], v[224:227], v[76:79]
	v_mfma_f32_16x16x32_bf16 v[68:71], v[144:147], v[224:227], v[68:71]
	v_mfma_f32_16x16x32_bf16 v[124:127], v[140:143], v[190:193], v[124:127]
	v_mfma_f32_16x16x32_bf16 v[116:119], v[148:151], v[190:193], v[116:119]
	v_mfma_f32_16x16x32_bf16 v[108:111], v[140:143], v[198:201], v[108:111]
	v_mfma_f32_16x16x32_bf16 v[100:103], v[148:151], v[198:201], v[100:103]
	v_mfma_f32_16x16x32_bf16 v[92:95], v[140:143], v[206:209], v[92:95]
	v_mfma_f32_16x16x32_bf16 v[84:87], v[148:151], v[206:209], v[84:87]
	v_mfma_f32_16x16x32_bf16 v[76:79], v[140:143], v[228:231], v[76:79]
	v_mfma_f32_16x16x32_bf16 v[68:71], v[148:151], v[228:231], v[68:71]
	s_barrier
	s_add_i32 s33, 0, 0x1c000
	s_add_i32 s3, s3, s61
	v_lshl_add_u64 v[152:153], v[152:153], 0, s[86:87]
	s_mov_b32 m0, s3
	ds_read_b128 v[232:235], v255
	ds_read_b128 v[236:239], v255 offset:1024
	ds_read_b128 v[240:243], v255 offset:2048
	ds_read_b128 v[244:247], v255 offset:3072
	global_load_lds_dwordx4 v[152:153], off
	s_add_i32 m0, s3, 0x2000
	v_lshl_add_u64 v[152:153], v[248:249], 0, s[86:87]
	global_load_lds_dwordx4 v[152:153], off
	s_barrier
	s_waitcnt lgkmcnt(0)
	v_mfma_f32_16x16x32_bf16 v[120:123], v[232:235], v[172:175], v[120:123]
	v_mfma_f32_16x16x32_bf16 v[112:115], v[240:243], v[172:175], v[112:115]
	v_mfma_f32_16x16x32_bf16 v[104:107], v[232:235], v[194:197], v[104:107]
	v_mfma_f32_16x16x32_bf16 v[96:99], v[240:243], v[194:197], v[96:99]
	v_mfma_f32_16x16x32_bf16 v[88:91], v[232:235], v[202:205], v[88:91]
	v_mfma_f32_16x16x32_bf16 v[80:83], v[240:243], v[202:205], v[80:83]
	v_mfma_f32_16x16x32_bf16 v[72:75], v[232:235], v[224:227], v[72:75]
	v_mfma_f32_16x16x32_bf16 v[64:67], v[240:243], v[224:227], v[64:67]
	v_mfma_f32_16x16x32_bf16 v[120:123], v[236:239], v[190:193], v[120:123]
	v_mfma_f32_16x16x32_bf16 v[112:115], v[244:247], v[190:193], v[112:115]
	v_mfma_f32_16x16x32_bf16 v[104:107], v[236:239], v[198:201], v[104:107]
	v_mfma_f32_16x16x32_bf16 v[96:99], v[244:247], v[198:201], v[96:99]
	v_mfma_f32_16x16x32_bf16 v[88:91], v[236:239], v[206:209], v[88:91]
	v_mfma_f32_16x16x32_bf16 v[80:83], v[244:247], v[206:209], v[80:83]
	v_mfma_f32_16x16x32_bf16 v[72:75], v[236:239], v[228:231], v[72:75]
	v_mfma_f32_16x16x32_bf16 v[64:67], v[244:247], v[228:231], v[64:67]
	s_mov_b32 m0, s67
	v_lshl_add_u64 v[152:153], v[250:251], 0, s[86:87]
	s_barrier
	ds_read_b128 v[172:175], v168 offset:49152
	ds_read_b128 v[190:193], v168 offset:50176
	ds_read_b128 v[194:197], v168 offset:51200
	ds_read_b128 v[198:201], v168 offset:52224
	ds_read_b128 v[202:205], v168 offset:53248
	ds_read_b128 v[206:209], v168 offset:54272
	ds_read_b128 v[224:227], v168 offset:55296
	ds_read_b128 v[228:231], v168 offset:56320
	global_load_lds_dwordx4 v[152:153], off
	s_mov_b32 m0, s68
	v_lshl_add_u64 v[152:153], v[252:253], 0, s[86:87]
	global_load_lds_dwordx4 v[152:153], off
	s_barrier
	s_waitcnt lgkmcnt(0)
	v_mfma_f32_16x16x32_bf16 v[60:63], v[136:139], v[172:175], v[60:63]
	v_mfma_f32_16x16x32_bf16 v[52:55], v[144:147], v[172:175], v[52:55]
	v_mfma_f32_16x16x32_bf16 v[44:47], v[136:139], v[194:197], v[44:47]
	v_mfma_f32_16x16x32_bf16 v[36:39], v[144:147], v[194:197], v[36:39]
	v_mfma_f32_16x16x32_bf16 v[28:31], v[136:139], v[202:205], v[28:31]
	v_mfma_f32_16x16x32_bf16 v[20:23], v[144:147], v[202:205], v[20:23]
	v_mfma_f32_16x16x32_bf16 v[12:15], v[136:139], v[224:227], v[12:15]
	v_mfma_f32_16x16x32_bf16 v[4:7], v[144:147], v[224:227], v[4:7]
	v_mfma_f32_16x16x32_bf16 v[60:63], v[140:143], v[190:193], v[60:63]
	v_mfma_f32_16x16x32_bf16 v[52:55], v[148:151], v[190:193], v[52:55]
	v_mfma_f32_16x16x32_bf16 v[44:47], v[140:143], v[198:201], v[44:47]
	v_mfma_f32_16x16x32_bf16 v[36:39], v[148:151], v[198:201], v[36:39]
	v_mfma_f32_16x16x32_bf16 v[28:31], v[140:143], v[206:209], v[28:31]
	v_mfma_f32_16x16x32_bf16 v[20:23], v[148:151], v[206:209], v[20:23]
	v_mfma_f32_16x16x32_bf16 v[12:15], v[140:143], v[228:231], v[12:15]
	v_mfma_f32_16x16x32_bf16 v[4:7], v[148:151], v[228:231], v[4:7]
	s_barrier
	s_add_u32 s28, s28, 0x80080
	s_addc_u32 s29, s29, 0
	s_add_i32 s3, s33, s61
	s_mov_b32 m0, s3
	v_lshl_add_u64 v[136:137], s[28:29], 0, v[184:185]
	global_load_lds_dwordx4 v[136:137], off
	s_add_i32 m0, s3, 0x2000
	v_lshl_add_u64 v[136:137], s[28:29], 0, v[188:189]
	global_load_lds_dwordx4 v[136:137], off
	s_waitcnt vmcnt(6)
	s_barrier
	v_mfma_f32_16x16x32_bf16 v[56:59], v[232:235], v[172:175], v[56:59]
	v_mfma_f32_16x16x32_bf16 v[48:51], v[240:243], v[172:175], v[48:51]
	v_mfma_f32_16x16x32_bf16 v[40:43], v[232:235], v[194:197], v[40:43]
	v_mfma_f32_16x16x32_bf16 v[32:35], v[240:243], v[194:197], v[32:35]
	v_mfma_f32_16x16x32_bf16 v[24:27], v[232:235], v[202:205], v[24:27]
	v_mfma_f32_16x16x32_bf16 v[16:19], v[240:243], v[202:205], v[16:19]
	v_mfma_f32_16x16x32_bf16 v[8:11], v[232:235], v[224:227], v[8:11]
	v_mfma_f32_16x16x32_bf16 v[0:3], v[240:243], v[224:227], v[0:3]
	v_mfma_f32_16x16x32_bf16 v[56:59], v[236:239], v[190:193], v[56:59]
	v_mfma_f32_16x16x32_bf16 v[48:51], v[244:247], v[190:193], v[48:51]
	v_mfma_f32_16x16x32_bf16 v[40:43], v[236:239], v[198:201], v[40:43]
	v_mfma_f32_16x16x32_bf16 v[32:35], v[244:247], v[198:201], v[32:35]
	v_mfma_f32_16x16x32_bf16 v[24:27], v[236:239], v[206:209], v[24:27]
	v_mfma_f32_16x16x32_bf16 v[16:19], v[244:247], v[206:209], v[16:19]
	v_mfma_f32_16x16x32_bf16 v[8:11], v[236:239], v[228:231], v[8:11]
	v_mfma_f32_16x16x32_bf16 v[0:3], v[244:247], v[228:231], v[0:3]
	s_add_i32 vcc_lo, vcc_lo, 2
	s_add_u32 s10, s10, 0x100
	s_addc_u32 s11, s11, 0
	s_add_u32 s93, s93, 0x100
	s_addc_u32 s95, s95, 0
	s_cmp_gt_u32 vcc_lo, 29
	s_barrier
	s_cbranch_scc1 .Lpeel_done_in
.LBB0_234:
	ds_read_b128 v[136:139], v167
	ds_read_b128 v[140:143], v167 offset:1024
	ds_read_b128 v[144:147], v167 offset:2048
	ds_read_b128 v[148:151], v167 offset:3072
	s_add_u32 s3, s10, 0xfff80080
	s_addc_u32 s28, s11, -1
	s_cmp_eq_u32 vcc_lo, 28
	s_cselect_b32 s35, s9, s28
	s_cselect_b32 s34, s89, s3
	s_cselect_b32 s29, s71, s95
	s_cselect_b32 s28, s91, s93
	v_lshl_add_u64 v[152:153], s[10:11], 0, v[132:133]
	s_add_i32 m0, s62, 0xc000
	ds_read_b128 v[172:175], v168
	ds_read_b128 v[190:193], v168 offset:1024
	ds_read_b128 v[194:197], v168 offset:2048
	ds_read_b128 v[198:201], v168 offset:3072
	ds_read_b128 v[202:205], v168 offset:4096
	ds_read_b128 v[206:209], v168 offset:5120
	ds_read_b128 v[224:227], v168 offset:6144
	ds_read_b128 v[228:231], v168 offset:7168
	global_load_lds_dwordx4 v[152:153], off
	s_add_i32 m0, s62, 0xe000
	v_lshl_add_u64 v[152:153], s[10:11], 0, v[134:135]
	global_load_lds_dwordx4 v[152:153], off
	s_waitcnt lgkmcnt(8)
	s_barrier
	s_waitcnt lgkmcnt(0)
	v_mfma_f32_16x16x32_bf16 v[124:127], v[136:139], v[172:175], v[124:127]
	v_mfma_f32_16x16x32_bf16 v[116:119], v[144:147], v[172:175], v[116:119]
	v_mfma_f32_16x16x32_bf16 v[108:111], v[136:139], v[194:197], v[108:111]
	v_mfma_f32_16x16x32_bf16 v[100:103], v[144:147], v[194:197], v[100:103]
	v_mfma_f32_16x16x32_bf16 v[92:95], v[136:139], v[202:205], v[92:95]
	v_mfma_f32_16x16x32_bf16 v[84:87], v[144:147], v[202:205], v[84:87]
	v_mfma_f32_16x16x32_bf16 v[76:79], v[136:139], v[224:227], v[76:79]
	v_mfma_f32_16x16x32_bf16 v[68:71], v[144:147], v[224:227], v[68:71]
	v_mfma_f32_16x16x32_bf16 v[124:127], v[140:143], v[190:193], v[124:127]
	v_mfma_f32_16x16x32_bf16 v[116:119], v[148:151], v[190:193], v[116:119]
	v_mfma_f32_16x16x32_bf16 v[108:111], v[140:143], v[198:201], v[108:111]
	v_mfma_f32_16x16x32_bf16 v[100:103], v[148:151], v[198:201], v[100:103]
	v_mfma_f32_16x16x32_bf16 v[92:95], v[140:143], v[206:209], v[92:95]
	v_mfma_f32_16x16x32_bf16 v[84:87], v[148:151], v[206:209], v[84:87]
	v_mfma_f32_16x16x32_bf16 v[76:79], v[140:143], v[228:231], v[76:79]
	v_mfma_f32_16x16x32_bf16 v[68:71], v[148:151], v[228:231], v[68:71]
	s_barrier
	s_add_i32 s3, s84, s61
	v_lshl_add_u64 v[152:153], s[28:29], 0, v[184:185]
	s_mov_b32 m0, s3
	ds_read_b128 v[232:235], v169
	ds_read_b128 v[236:239], v169 offset:1024
	ds_read_b128 v[240:243], v169 offset:2048
	ds_read_b128 v[244:247], v169 offset:3072
	global_load_lds_dwordx4 v[152:153], off
	s_add_i32 m0, s3, 0x2000
	v_lshl_add_u64 v[248:249], s[28:29], 0, v[188:189]
	global_load_lds_dwordx4 v[248:249], off
	s_barrier
	s_waitcnt lgkmcnt(0)
	v_mfma_f32_16x16x32_bf16 v[120:123], v[232:235], v[172:175], v[120:123]
	v_mfma_f32_16x16x32_bf16 v[112:115], v[240:243], v[172:175], v[112:115]
	v_mfma_f32_16x16x32_bf16 v[104:107], v[232:235], v[194:197], v[104:107]
	v_mfma_f32_16x16x32_bf16 v[96:99], v[240:243], v[194:197], v[96:99]
	v_mfma_f32_16x16x32_bf16 v[88:91], v[232:235], v[202:205], v[88:91]
	v_mfma_f32_16x16x32_bf16 v[80:83], v[240:243], v[202:205], v[80:83]
	v_mfma_f32_16x16x32_bf16 v[72:75], v[232:235], v[224:227], v[72:75]
	v_mfma_f32_16x16x32_bf16 v[64:67], v[240:243], v[224:227], v[64:67]
	v_mfma_f32_16x16x32_bf16 v[120:123], v[236:239], v[190:193], v[120:123]
	v_mfma_f32_16x16x32_bf16 v[112:115], v[244:247], v[190:193], v[112:115]
	v_mfma_f32_16x16x32_bf16 v[104:107], v[236:239], v[198:201], v[104:107]
	v_mfma_f32_16x16x32_bf16 v[96:99], v[244:247], v[198:201], v[96:99]
	v_mfma_f32_16x16x32_bf16 v[88:91], v[236:239], v[206:209], v[88:91]
	v_mfma_f32_16x16x32_bf16 v[80:83], v[244:247], v[206:209], v[80:83]
	v_mfma_f32_16x16x32_bf16 v[72:75], v[236:239], v[228:231], v[72:75]
	v_mfma_f32_16x16x32_bf16 v[64:67], v[244:247], v[228:231], v[64:67]
	s_mov_b32 m0, s62
	v_lshl_add_u64 v[250:251], s[34:35], 0, v[182:183]
	s_barrier
	ds_read_b128 v[172:175], v168 offset:16384
	ds_read_b128 v[190:193], v168 offset:17408
	ds_read_b128 v[194:197], v168 offset:18432
	ds_read_b128 v[198:201], v168 offset:19456
	ds_read_b128 v[202:205], v168 offset:20480
	ds_read_b128 v[206:209], v168 offset:21504
	ds_read_b128 v[224:227], v168 offset:22528
	ds_read_b128 v[228:231], v168 offset:23552
	global_load_lds_dwordx4 v[250:251], off
	s_mov_b32 m0, s63
	v_lshl_add_u64 v[252:253], s[34:35], 0, v[186:187]
	global_load_lds_dwordx4 v[252:253], off
	s_barrier
	s_waitcnt lgkmcnt(0)
	v_mfma_f32_16x16x32_bf16 v[60:63], v[136:139], v[172:175], v[60:63]
	v_mfma_f32_16x16x32_bf16 v[52:55], v[144:147], v[172:175], v[52:55]
	v_mfma_f32_16x16x32_bf16 v[44:47], v[136:139], v[194:197], v[44:47]
	v_mfma_f32_16x16x32_bf16 v[36:39], v[144:147], v[194:197], v[36:39]
	v_mfma_f32_16x16x32_bf16 v[28:31], v[136:139], v[202:205], v[28:31]
	v_mfma_f32_16x16x32_bf16 v[20:23], v[144:147], v[202:205], v[20:23]
	v_mfma_f32_16x16x32_bf16 v[12:15], v[136:139], v[224:227], v[12:15]
	v_mfma_f32_16x16x32_bf16 v[4:7], v[144:147], v[224:227], v[4:7]
	v_mfma_f32_16x16x32_bf16 v[60:63], v[140:143], v[190:193], v[60:63]
	v_mfma_f32_16x16x32_bf16 v[52:55], v[148:151], v[190:193], v[52:55]
	v_mfma_f32_16x16x32_bf16 v[44:47], v[140:143], v[198:201], v[44:47]
	v_mfma_f32_16x16x32_bf16 v[36:39], v[148:151], v[198:201], v[36:39]
	v_mfma_f32_16x16x32_bf16 v[28:31], v[140:143], v[206:209], v[28:31]
	v_mfma_f32_16x16x32_bf16 v[20:23], v[148:151], v[206:209], v[20:23]
	v_mfma_f32_16x16x32_bf16 v[12:15], v[140:143], v[228:231], v[12:15]
	v_mfma_f32_16x16x32_bf16 v[4:7], v[148:151], v[228:231], v[4:7]
	s_barrier
	s_add_u32 s74, s28, 0x80000
	s_addc_u32 s75, s29, 0
	s_add_i32 s3, s85, s61
	s_mov_b32 m0, s3
	v_lshl_add_u64 v[136:137], s[74:75], 0, v[184:185]
	global_load_lds_dwordx4 v[136:137], off
	s_add_i32 m0, s3, 0x2000
	v_lshl_add_u64 v[136:137], s[74:75], 0, v[188:189]
	global_load_lds_dwordx4 v[136:137], off
	s_waitcnt vmcnt(6)
	s_barrier
	v_mfma_f32_16x16x32_bf16 v[56:59], v[232:235], v[172:175], v[56:59]
	v_mfma_f32_16x16x32_bf16 v[48:51], v[240:243], v[172:175], v[48:51]
	v_mfma_f32_16x16x32_bf16 v[40:43], v[232:235], v[194:197], v[40:43]
	v_mfma_f32_16x16x32_bf16 v[32:35], v[240:243], v[194:197], v[32:35]
	v_mfma_f32_16x16x32_bf16 v[24:27], v[232:235], v[202:205], v[24:27]
	v_mfma_f32_16x16x32_bf16 v[16:19], v[240:243], v[202:205], v[16:19]
	v_mfma_f32_16x16x32_bf16 v[8:11], v[232:235], v[224:227], v[8:11]
	v_mfma_f32_16x16x32_bf16 v[0:3], v[240:243], v[224:227], v[0:3]
	v_mfma_f32_16x16x32_bf16 v[56:59], v[236:239], v[190:193], v[56:59]
	v_mfma_f32_16x16x32_bf16 v[48:51], v[244:247], v[190:193], v[48:51]
	v_mfma_f32_16x16x32_bf16 v[40:43], v[236:239], v[198:201], v[40:43]
	v_mfma_f32_16x16x32_bf16 v[32:35], v[244:247], v[198:201], v[32:35]
	v_mfma_f32_16x16x32_bf16 v[24:27], v[236:239], v[206:209], v[24:27]
	v_mfma_f32_16x16x32_bf16 v[16:19], v[244:247], v[206:209], v[16:19]
	v_mfma_f32_16x16x32_bf16 v[8:11], v[236:239], v[228:231], v[8:11]
	v_mfma_f32_16x16x32_bf16 v[0:3], v[244:247], v[228:231], v[0:3]
	s_add_i32 s3, 0, 0x18000
	s_barrier
	ds_read_b128 v[136:139], v171
	ds_read_b128 v[140:143], v171 offset:1024
	ds_read_b128 v[144:147], v171 offset:2048
	ds_read_b128 v[148:151], v171 offset:3072
	s_add_u32 s34, s34, 0x80000
	s_addc_u32 s35, s35, 0
	s_mov_b32 m0, s64
	v_lshl_add_u64 v[232:233], s[34:35], 0, v[182:183]
	ds_read_b128 v[172:175], v168 offset:32768
	ds_read_b128 v[190:193], v168 offset:33792
	ds_read_b128 v[194:197], v168 offset:34816
	ds_read_b128 v[198:201], v168 offset:35840
	ds_read_b128 v[202:205], v168 offset:36864
	ds_read_b128 v[206:209], v168 offset:37888
	ds_read_b128 v[224:227], v168 offset:38912
	ds_read_b128 v[228:231], v168 offset:39936
	global_load_lds_dwordx4 v[232:233], off
	s_mov_b32 m0, s65
	v_lshl_add_u64 v[232:233], s[34:35], 0, v[186:187]
	global_load_lds_dwordx4 v[232:233], off
	s_waitcnt lgkmcnt(8)
	s_barrier
	s_waitcnt lgkmcnt(0)
	v_mfma_f32_16x16x32_bf16 v[124:127], v[136:139], v[172:175], v[124:127]
	v_mfma_f32_16x16x32_bf16 v[116:119], v[144:147], v[172:175], v[116:119]
	v_mfma_f32_16x16x32_bf16 v[108:111], v[136:139], v[194:197], v[108:111]
	v_mfma_f32_16x16x32_bf16 v[100:103], v[144:147], v[194:197], v[100:103]
	v_mfma_f32_16x16x32_bf16 v[92:95], v[136:139], v[202:205], v[92:95]
	v_mfma_f32_16x16x32_bf16 v[84:87], v[144:147], v[202:205], v[84:87]
	v_mfma_f32_16x16x32_bf16 v[76:79], v[136:139], v[224:227], v[76:79]
	v_mfma_f32_16x16x32_bf16 v[68:71], v[144:147], v[224:227], v[68:71]
	v_mfma_f32_16x16x32_bf16 v[124:127], v[140:143], v[190:193], v[124:127]
	v_mfma_f32_16x16x32_bf16 v[116:119], v[148:151], v[190:193], v[116:119]
	v_mfma_f32_16x16x32_bf16 v[108:111], v[140:143], v[198:201], v[108:111]
	v_mfma_f32_16x16x32_bf16 v[100:103], v[148:151], v[198:201], v[100:103]
	v_mfma_f32_16x16x32_bf16 v[92:95], v[140:143], v[206:209], v[92:95]
	v_mfma_f32_16x16x32_bf16 v[84:87], v[148:151], v[206:209], v[84:87]
	v_mfma_f32_16x16x32_bf16 v[76:79], v[140:143], v[228:231], v[76:79]
	v_mfma_f32_16x16x32_bf16 v[68:71], v[148:151], v[228:231], v[68:71]
	s_barrier
	s_add_i32 s33, 0, 0x1c000
	s_add_i32 s3, s3, s61
	v_lshl_add_u64 v[152:153], v[152:153], 0, s[86:87]
	s_mov_b32 m0, s3
	ds_read_b128 v[232:235], v255
	ds_read_b128 v[236:239], v255 offset:1024
	ds_read_b128 v[240:243], v255 offset:2048
	ds_read_b128 v[244:247], v255 offset:3072
	global_load_lds_dwordx4 v[152:153], off
	s_add_i32 m0, s3, 0x2000
	v_lshl_add_u64 v[152:153], v[248:249], 0, s[86:87]
	global_load_lds_dwordx4 v[152:153], off
	s_barrier
	s_waitcnt lgkmcnt(0)
	v_mfma_f32_16x16x32_bf16 v[120:123], v[232:235], v[172:175], v[120:123]
	v_mfma_f32_16x16x32_bf16 v[112:115], v[240:243], v[172:175], v[112:115]
	v_mfma_f32_16x16x32_bf16 v[104:107], v[232:235], v[194:197], v[104:107]
	v_mfma_f32_16x16x32_bf16 v[96:99], v[240:243], v[194:197], v[96:99]
	v_mfma_f32_16x16x32_bf16 v[88:91], v[232:235], v[202:205], v[88:91]
	v_mfma_f32_16x16x32_bf16 v[80:83], v[240:243], v[202:205], v[80:83]
	v_mfma_f32_16x16x32_bf16 v[72:75], v[232:235], v[224:227], v[72:75]
	v_mfma_f32_16x16x32_bf16 v[64:67], v[240:243], v[224:227], v[64:67]
	v_mfma_f32_16x16x32_bf16 v[120:123], v[236:239], v[190:193], v[120:123]
	v_mfma_f32_16x16x32_bf16 v[112:115], v[244:247], v[190:193], v[112:115]
	v_mfma_f32_16x16x32_bf16 v[104:107], v[236:239], v[198:201], v[104:107]
	v_mfma_f32_16x16x32_bf16 v[96:99], v[244:247], v[198:201], v[96:99]
	v_mfma_f32_16x16x32_bf16 v[88:91], v[236:239], v[206:209], v[88:91]
	v_mfma_f32_16x16x32_bf16 v[80:83], v[244:247], v[206:209], v[80:83]
	v_mfma_f32_16x16x32_bf16 v[72:75], v[236:239], v[228:231], v[72:75]
	v_mfma_f32_16x16x32_bf16 v[64:67], v[244:247], v[228:231], v[64:67]
	s_mov_b32 m0, s67
	v_lshl_add_u64 v[152:153], v[250:251], 0, s[86:87]
	s_barrier
	ds_read_b128 v[172:175], v168 offset:49152
	ds_read_b128 v[190:193], v168 offset:50176
	ds_read_b128 v[194:197], v168 offset:51200
	ds_read_b128 v[198:201], v168 offset:52224
	ds_read_b128 v[202:205], v168 offset:53248
	ds_read_b128 v[206:209], v168 offset:54272
	ds_read_b128 v[224:227], v168 offset:55296
	ds_read_b128 v[228:231], v168 offset:56320
	global_load_lds_dwordx4 v[152:153], off
	s_mov_b32 m0, s68
	v_lshl_add_u64 v[152:153], v[252:253], 0, s[86:87]
	global_load_lds_dwordx4 v[152:153], off
	s_barrier
	s_waitcnt lgkmcnt(0)
	v_mfma_f32_16x16x32_bf16 v[60:63], v[136:139], v[172:175], v[60:63]
	v_mfma_f32_16x16x32_bf16 v[52:55], v[144:147], v[172:175], v[52:55]
	v_mfma_f32_16x16x32_bf16 v[44:47], v[136:139], v[194:197], v[44:47]
	v_mfma_f32_16x16x32_bf16 v[36:39], v[144:147], v[194:197], v[36:39]
	v_mfma_f32_16x16x32_bf16 v[28:31], v[136:139], v[202:205], v[28:31]
	v_mfma_f32_16x16x32_bf16 v[20:23], v[144:147], v[202:205], v[20:23]
	v_mfma_f32_16x16x32_bf16 v[12:15], v[136:139], v[224:227], v[12:15]
	v_mfma_f32_16x16x32_bf16 v[4:7], v[144:147], v[224:227], v[4:7]
	v_mfma_f32_16x16x32_bf16 v[60:63], v[140:143], v[190:193], v[60:63]
	v_mfma_f32_16x16x32_bf16 v[52:55], v[148:151], v[190:193], v[52:55]
	v_mfma_f32_16x16x32_bf16 v[44:47], v[140:143], v[198:201], v[44:47]
	v_mfma_f32_16x16x32_bf16 v[36:39], v[148:151], v[198:201], v[36:39]
	v_mfma_f32_16x16x32_bf16 v[28:31], v[140:143], v[206:209], v[28:31]
	v_mfma_f32_16x16x32_bf16 v[20:23], v[148:151], v[206:209], v[20:23]
	v_mfma_f32_16x16x32_bf16 v[12:15], v[140:143], v[228:231], v[12:15]
	v_mfma_f32_16x16x32_bf16 v[4:7], v[148:151], v[228:231], v[4:7]
	s_barrier
	s_add_u32 s28, s28, 0x80080
	s_addc_u32 s29, s29, 0
	s_add_i32 s3, s33, s61
	s_mov_b32 m0, s3
	v_lshl_add_u64 v[136:137], s[28:29], 0, v[184:185]
	global_load_lds_dwordx4 v[136:137], off
	s_add_i32 m0, s3, 0x2000
	v_lshl_add_u64 v[136:137], s[28:29], 0, v[188:189]
	global_load_lds_dwordx4 v[136:137], off
	s_waitcnt vmcnt(6)
	s_barrier
	v_mfma_f32_16x16x32_bf16 v[56:59], v[232:235], v[172:175], v[56:59]
	v_mfma_f32_16x16x32_bf16 v[48:51], v[240:243], v[172:175], v[48:51]
	v_mfma_f32_16x16x32_bf16 v[40:43], v[232:235], v[194:197], v[40:43]
	v_mfma_f32_16x16x32_bf16 v[32:35], v[240:243], v[194:197], v[32:35]
	v_mfma_f32_16x16x32_bf16 v[24:27], v[232:235], v[202:205], v[24:27]
	v_mfma_f32_16x16x32_bf16 v[16:19], v[240:243], v[202:205], v[16:19]
	v_mfma_f32_16x16x32_bf16 v[8:11], v[232:235], v[224:227], v[8:11]
	v_mfma_f32_16x16x32_bf16 v[0:3], v[240:243], v[224:227], v[0:3]
	v_mfma_f32_16x16x32_bf16 v[56:59], v[236:239], v[190:193], v[56:59]
	v_mfma_f32_16x16x32_bf16 v[48:51], v[244:247], v[190:193], v[48:51]
	v_mfma_f32_16x16x32_bf16 v[40:43], v[236:239], v[198:201], v[40:43]
	v_mfma_f32_16x16x32_bf16 v[32:35], v[244:247], v[198:201], v[32:35]
	v_mfma_f32_16x16x32_bf16 v[24:27], v[236:239], v[206:209], v[24:27]
	v_mfma_f32_16x16x32_bf16 v[16:19], v[244:247], v[206:209], v[16:19]
	v_mfma_f32_16x16x32_bf16 v[8:11], v[236:239], v[228:231], v[8:11]
	v_mfma_f32_16x16x32_bf16 v[0:3], v[244:247], v[228:231], v[0:3]
	s_add_i32 vcc_lo, vcc_lo, 2
	s_add_u32 s10, s10, 0x100
	s_addc_u32 s11, s11, 0
	s_add_u32 s93, s93, 0x100
	s_addc_u32 s95, s95, 0
	s_cmp_gt_u32 vcc_lo, 29
	s_barrier
	s_cbranch_scc0 .LBB0_234

	.amdhsa_kernel _Z9hymba_fwd6Params
		.amdhsa_group_segment_fixed_size 0
		.amdhsa_private_segment_fixed_size 0
		.amdhsa_kernarg_size 440
		.amdhsa_user_sgpr_count 2
		.amdhsa_user_sgpr_dispatch_ptr 0
		.amdhsa_user_sgpr_queue_ptr 0
		.amdhsa_user_sgpr_kernarg_segment_ptr 1
		.amdhsa_user_sgpr_dispatch_id 0
		.amdhsa_user_sgpr_kernarg_preload_length 0
		.amdhsa_user_sgpr_kernarg_preload_offset 0
		.amdhsa_user_sgpr_private_segment_size 0
		.amdhsa_uses_dynamic_stack 0
		.amdhsa_enable_private_segment 0
		.amdhsa_system_sgpr_workgroup_id_x 1
		.amdhsa_system_sgpr_workgroup_id_y 0
		.amdhsa_system_sgpr_workgroup_id_z 0
		.amdhsa_system_sgpr_workgroup_info 0
		.amdhsa_system_vgpr_workitem_id 2
		.amdhsa_next_free_vgpr 256
		.amdhsa_next_free_sgpr 100
		.amdhsa_accum_offset 256
		.amdhsa_reserve_vcc 1
		.amdhsa_float_round_mode_32 0
		.amdhsa_float_round_mode_16_64 0
		.amdhsa_float_denorm_mode_32 3
		.amdhsa_float_denorm_mode_16_64 3
		.amdhsa_dx10_clamp 1
		.amdhsa_ieee_mode 1
		.amdhsa_fp16_overflow 0
		.amdhsa_tg_split 0
		.amdhsa_exception_fp_ieee_invalid_op 0
		.amdhsa_exception_fp_denorm_src 0
		.amdhsa_exception_fp_ieee_div_zero 0
		.amdhsa_exception_fp_ieee_overflow 0
		.amdhsa_exception_fp_ieee_underflow 0
		.amdhsa_exception_fp_ieee_inexact 0
		.amdhsa_exception_int_div_zero 0
	.end_amdhsa_kernel

.Lfunc_end0:
	.size	_Z9hymba_fwd6Params, .Lfunc_end0-_Z9hymba_fwd6Params
	.set _Z9hymba_fwd6Params.num_vgpr, 256
	.set _Z9hymba_fwd6Params.num_agpr, 0
	.set _Z9hymba_fwd6Params.numbered_sgpr, 100
	.set _Z9hymba_fwd6Params.num_named_barrier, 0
	.set _Z9hymba_fwd6Params.private_seg_size, 0
	.set _Z9hymba_fwd6Params.uses_vcc, 1
	.set _Z9hymba_fwd6Params.uses_flat_scratch, 0
	.set _Z9hymba_fwd6Params.has_dyn_sized_stack, 0
	.set _Z9hymba_fwd6Params.has_recursion, 0
	.set _Z9hymba_fwd6Params.has_indirect_call, 0

amdhsa.kernels:
  - .agpr_count:     0
    .args:
      - .offset:         0
        .size:           184
        .value_kind:     by_value
      - .offset:         184
        .size:           4
        .value_kind:     hidden_block_count_x
      - .offset:         188
        .size:           4
        .value_kind:     hidden_block_count_y
      - .offset:         192
        .size:           4
        .value_kind:     hidden_block_count_z
      - .offset:         196
        .size:           2
        .value_kind:     hidden_group_size_x
      - .offset:         198
        .size:           2
        .value_kind:     hidden_group_size_y
      - .offset:         200
        .size:           2
        .value_kind:     hidden_group_size_z
      - .offset:         202
        .size:           2
        .value_kind:     hidden_remainder_x
      - .offset:         204
        .size:           2
        .value_kind:     hidden_remainder_y
      - .offset:         206
        .size:           2
        .value_kind:     hidden_remainder_z
      - .offset:         224
        .size:           8
        .value_kind:     hidden_global_offset_x
      - .offset:         232
        .size:           8
        .value_kind:     hidden_global_offset_y
      - .offset:         240
        .size:           8
        .value_kind:     hidden_global_offset_z
      - .offset:         248
        .size:           2
        .value_kind:     hidden_grid_dims
      - .offset:         272
        .size:           8
        .value_kind:     hidden_multigrid_sync_arg
      - .offset:         304
        .size:           4
        .value_kind:     hidden_dynamic_lds_size
    .group_segment_fixed_size: 0
    .kernarg_segment_align: 8
    .kernarg_segment_size: 440
    .language:       OpenCL C
    .language_version:
      - 2
      - 0
    .max_flat_workgroup_size: 512
    .name:           _Z9hymba_fwd6Params
    .private_segment_fixed_size: 0
    .sgpr_count:     106
    .sgpr_spill_count: 33
    .symbol:         _Z9hymba_fwd6Params.kd
    .uniform_work_group_size: 1
    .uses_dynamic_stack: false
    .vgpr_count:     256
    .vgpr_spill_count: 0
    .wavefront_size: 64
